# PEER table f32->fp8 conversion rewritten: 16 loads per batch, two batches in flight per wave (was one 4-load item at a time)
# speedup vs baseline: 1.0060x; 1.0053x over previous
; DI void phase_tables(const Params& p, int l, int bid, int nblk) {
;     ...
;   for (int e = gtid; e < 2 * 16384 * 64; e += gn) {
;     const int which = e / (16384 * 64), r = e % (16384 * 64);
;     const float sc = which ? V_SCALE : U_SCALE;
;     const float* src = (which ? p.in[I_PV] : p.in[I_PU]) + (size_t)l * 16384 * 1024 + (size_t)r * 16;
;     u32 o[4];
; #pragma unroll
;     for (int q = 0; q < 4; ++q) {
;       const float4 a = *(const float4*)(src + q * 4);
;       int v = __builtin_amdgcn_cvt_pk_fp8_f32(a.x * sc, a.y * sc, 0, false);
;       v = __builtin_amdgcn_cvt_pk_fp8_f32(a.z * sc, a.w * sc, v, true);
;       o[q] = (u32)v;
;     }
;     uint4 ov = {o[0], o[1], o[2], o[3]};
;     *(uint4*)&dst[(size_t)e * 16] = ov;
;   }
.LBB0_1330:
	s_or_b64 exec, exec, s[34:35]
	v_readlane_b32 s19, v255, 54
	v_readlane_b32 s16, v255, 40
	v_readlane_b32 s17, v255, 41
	s_lshl_b32 s86, s24, 26
	v_add_u32_e32 v0, s19, v218
	v_lshlrev_b32_e32 v4, 6, v0
	v_bfe_u32 v1, v0, 3, 3
	v_lshlrev_b32_e32 v1, 21, v1
	v_bfe_u32 v2, v0, 6, 11
	v_lshl_or_b32 v1, v2, 7, v1
	v_and_b32_e32 v2, 7, v0
	v_lshl_or_b32 v5, v2, 4, v1
	s_add_u32 s22, s88, s86
	s_addc_u32 s23, s89, 0
	global_load_dwordx4 v[8:11], v4, s[22:23]
	global_load_dwordx4 v[12:15], v4, s[22:23] offset:16
	global_load_dwordx4 v[16:19], v4, s[22:23] offset:32
	global_load_dwordx4 v[20:23], v4, s[22:23] offset:48
	s_add_u32 s36, s22, 0x800000
	s_addc_u32 s37, s23, 0
	global_load_dwordx4 v[24:27], v4, s[36:37]
	global_load_dwordx4 v[28:31], v4, s[36:37] offset:16
	global_load_dwordx4 v[32:35], v4, s[36:37] offset:32
	global_load_dwordx4 v[36:39], v4, s[36:37] offset:48
	s_add_u32 s36, s22, 0x1000000
	s_addc_u32 s37, s23, 0
	global_load_dwordx4 v[40:43], v4, s[36:37]
	global_load_dwordx4 v[44:47], v4, s[36:37] offset:16
	global_load_dwordx4 v[48:51], v4, s[36:37] offset:32
	global_load_dwordx4 v[52:55], v4, s[36:37] offset:48
	s_add_u32 s36, s22, 0x1800000
	s_addc_u32 s37, s23, 0
	global_load_dwordx4 v[56:59], v4, s[36:37]
	global_load_dwordx4 v[60:63], v4, s[36:37] offset:16
	global_load_dwordx4 v[64:67], v4, s[36:37] offset:32
	global_load_dwordx4 v[68:71], v4, s[36:37] offset:48
	s_add_u32 s36, s22, 0x2000000
	s_addc_u32 s37, s23, 0
	global_load_dwordx4 v[72:75], v4, s[36:37]
	global_load_dwordx4 v[76:79], v4, s[36:37] offset:16
	global_load_dwordx4 v[80:83], v4, s[36:37] offset:32
	global_load_dwordx4 v[84:87], v4, s[36:37] offset:48
	s_add_u32 s36, s22, 0x2800000
	s_addc_u32 s37, s23, 0
	global_load_dwordx4 v[88:91], v4, s[36:37]
	global_load_dwordx4 v[92:95], v4, s[36:37] offset:16
	global_load_dwordx4 v[96:99], v4, s[36:37] offset:32
	global_load_dwordx4 v[100:103], v4, s[36:37] offset:48
	s_add_u32 s36, s22, 0x3000000
	s_addc_u32 s37, s23, 0
	global_load_dwordx4 v[104:107], v4, s[36:37]
	global_load_dwordx4 v[108:111], v4, s[36:37] offset:16
	global_load_dwordx4 v[112:115], v4, s[36:37] offset:32
	global_load_dwordx4 v[116:119], v4, s[36:37] offset:48
	s_add_u32 s36, s22, 0x3800000
	s_addc_u32 s37, s23, 0
	global_load_dwordx4 v[120:123], v4, s[36:37]
	global_load_dwordx4 v[124:127], v4, s[36:37] offset:16
	global_load_dwordx4 v[128:131], v4, s[36:37] offset:32
	global_load_dwordx4 v[132:135], v4, s[36:37] offset:48
	s_waitcnt vmcnt(16)
	v_mov_b32_e32 v6, 0x42800000
	v_mov_b32_e32 v7, v6
	v_pk_mul_f32 v[8:9], v[8:9], v[6:7]
	v_pk_mul_f32 v[10:11], v[10:11], v[6:7]
	v_cvt_pk_fp8_f32 v148, v8, v9
	v_cvt_pk_fp8_f32 v148, v10, v11 op_sel:[0,0,1]
	v_pk_mul_f32 v[12:13], v[12:13], v[6:7]
	v_pk_mul_f32 v[14:15], v[14:15], v[6:7]
	v_cvt_pk_fp8_f32 v149, v12, v13
	v_cvt_pk_fp8_f32 v149, v14, v15 op_sel:[0,0,1]
	v_pk_mul_f32 v[16:17], v[16:17], v[6:7]
	v_pk_mul_f32 v[18:19], v[18:19], v[6:7]
	v_cvt_pk_fp8_f32 v150, v16, v17
	v_cvt_pk_fp8_f32 v150, v18, v19 op_sel:[0,0,1]
	v_pk_mul_f32 v[20:21], v[20:21], v[6:7]
	v_pk_mul_f32 v[22:23], v[22:23], v[6:7]
	v_cvt_pk_fp8_f32 v151, v20, v21
	v_cvt_pk_fp8_f32 v151, v22, v23 op_sel:[0,0,1]
	s_add_u32 s38, s16, 0x0
	s_addc_u32 s39, s17, 0
	global_store_dwordx4 v5, v[148:151], s[38:39]
	v_pk_mul_f32 v[24:25], v[24:25], v[6:7]
	v_pk_mul_f32 v[26:27], v[26:27], v[6:7]
	v_cvt_pk_fp8_f32 v152, v24, v25
	v_cvt_pk_fp8_f32 v152, v26, v27 op_sel:[0,0,1]
	v_pk_mul_f32 v[28:29], v[28:29], v[6:7]
	v_pk_mul_f32 v[30:31], v[30:31], v[6:7]
	v_cvt_pk_fp8_f32 v153, v28, v29
	v_cvt_pk_fp8_f32 v153, v30, v31 op_sel:[0,0,1]
	v_pk_mul_f32 v[32:33], v[32:33], v[6:7]
	v_pk_mul_f32 v[34:35], v[34:35], v[6:7]
	v_cvt_pk_fp8_f32 v154, v32, v33
	v_cvt_pk_fp8_f32 v154, v34, v35 op_sel:[0,0,1]
	v_pk_mul_f32 v[36:37], v[36:37], v[6:7]
	v_pk_mul_f32 v[38:39], v[38:39], v[6:7]
	v_cvt_pk_fp8_f32 v155, v36, v37
	v_cvt_pk_fp8_f32 v155, v38, v39 op_sel:[0,0,1]
	s_add_u32 s38, s16, 0x40000
	s_addc_u32 s39, s17, 0
	global_store_dwordx4 v5, v[152:155], s[38:39]
	v_pk_mul_f32 v[40:41], v[40:41], v[6:7]
	v_pk_mul_f32 v[42:43], v[42:43], v[6:7]
	v_cvt_pk_fp8_f32 v156, v40, v41
	v_cvt_pk_fp8_f32 v156, v42, v43 op_sel:[0,0,1]
	v_pk_mul_f32 v[44:45], v[44:45], v[6:7]
	v_pk_mul_f32 v[46:47], v[46:47], v[6:7]
	v_cvt_pk_fp8_f32 v157, v44, v45
	v_cvt_pk_fp8_f32 v157, v46, v47 op_sel:[0,0,1]
	v_pk_mul_f32 v[48:49], v[48:49], v[6:7]
	v_pk_mul_f32 v[50:51], v[50:51], v[6:7]
	v_cvt_pk_fp8_f32 v158, v48, v49
	v_cvt_pk_fp8_f32 v158, v50, v51 op_sel:[0,0,1]
	v_pk_mul_f32 v[52:53], v[52:53], v[6:7]
	v_pk_mul_f32 v[54:55], v[54:55], v[6:7]
	v_cvt_pk_fp8_f32 v159, v52, v53
	v_cvt_pk_fp8_f32 v159, v54, v55 op_sel:[0,0,1]
	s_add_u32 s38, s16, 0x80000
	s_addc_u32 s39, s17, 0
	global_store_dwordx4 v5, v[156:159], s[38:39]
	v_pk_mul_f32 v[56:57], v[56:57], v[6:7]
	v_pk_mul_f32 v[58:59], v[58:59], v[6:7]
	v_cvt_pk_fp8_f32 v160, v56, v57
	v_cvt_pk_fp8_f32 v160, v58, v59 op_sel:[0,0,1]
	v_pk_mul_f32 v[60:61], v[60:61], v[6:7]
	v_pk_mul_f32 v[62:63], v[62:63], v[6:7]
	v_cvt_pk_fp8_f32 v161, v60, v61
	v_cvt_pk_fp8_f32 v161, v62, v63 op_sel:[0,0,1]
	v_pk_mul_f32 v[64:65], v[64:65], v[6:7]
	v_pk_mul_f32 v[66:67], v[66:67], v[6:7]
	v_cvt_pk_fp8_f32 v162, v64, v65
	v_cvt_pk_fp8_f32 v162, v66, v67 op_sel:[0,0,1]
	v_pk_mul_f32 v[68:69], v[68:69], v[6:7]
	v_pk_mul_f32 v[70:71], v[70:71], v[6:7]
	v_cvt_pk_fp8_f32 v163, v68, v69
	v_cvt_pk_fp8_f32 v163, v70, v71 op_sel:[0,0,1]
	s_add_u32 s38, s16, 0xc0000
	s_addc_u32 s39, s17, 0
	global_store_dwordx4 v5, v[160:163], s[38:39]
	s_add_u32 s22, s90, s86
	s_addc_u32 s23, s91, 0
	global_load_dwordx4 v[8:11], v4, s[22:23]
	global_load_dwordx4 v[12:15], v4, s[22:23] offset:16
	global_load_dwordx4 v[16:19], v4, s[22:23] offset:32
	global_load_dwordx4 v[20:23], v4, s[22:23] offset:48
	s_add_u32 s36, s22, 0x800000
	s_addc_u32 s37, s23, 0
	global_load_dwordx4 v[24:27], v4, s[36:37]
	global_load_dwordx4 v[28:31], v4, s[36:37] offset:16
	global_load_dwordx4 v[32:35], v4, s[36:37] offset:32
	global_load_dwordx4 v[36:39], v4, s[36:37] offset:48
	s_add_u32 s36, s22, 0x1000000
	s_addc_u32 s37, s23, 0
	global_load_dwordx4 v[40:43], v4, s[36:37]
	global_load_dwordx4 v[44:47], v4, s[36:37] offset:16
	global_load_dwordx4 v[48:51], v4, s[36:37] offset:32
	global_load_dwordx4 v[52:55], v4, s[36:37] offset:48
	s_add_u32 s36, s22, 0x1800000
	s_addc_u32 s37, s23, 0
	global_load_dwordx4 v[56:59], v4, s[36:37]
	global_load_dwordx4 v[60:63], v4, s[36:37] offset:16
	global_load_dwordx4 v[64:67], v4, s[36:37] offset:32
	global_load_dwordx4 v[68:71], v4, s[36:37] offset:48
	s_waitcnt vmcnt(20)
; DI void phase_tables(const Params& p, int l, int bid, int nblk) {
;     ...
;   for (int e = gtid; e < 2 * 16384 * 64; e += gn) {
;     const int which = e / (16384 * 64), r = e % (16384 * 64);
;     const float sc = which ? V_SCALE : U_SCALE;
;     const float* src = (which ? p.in[I_PV] : p.in[I_PU]) + (size_t)l * 16384 * 1024 + (size_t)r * 16;
;     u32 o[4];
; #pragma unroll
;     for (int q = 0; q < 4; ++q) {
;       const float4 a = *(const float4*)(src + q * 4);
;       int v = __builtin_amdgcn_cvt_pk_fp8_f32(a.x * sc, a.y * sc, 0, false);
;       v = __builtin_amdgcn_cvt_pk_fp8_f32(a.z * sc, a.w * sc, v, true);
;       o[q] = (u32)v;
;     }
;     uint4 ov = {o[0], o[1], o[2], o[3]};
;     *(uint4*)&dst[(size_t)e * 16] = ov;
;   }
	v_mov_b32_e32 v6, 0x42800000
	v_mov_b32_e32 v7, v6
	v_pk_mul_f32 v[72:73], v[72:73], v[6:7]
	v_pk_mul_f32 v[74:75], v[74:75], v[6:7]
	v_cvt_pk_fp8_f32 v176, v72, v73
	v_cvt_pk_fp8_f32 v176, v74, v75 op_sel:[0,0,1]
	v_pk_mul_f32 v[76:77], v[76:77], v[6:7]
	v_pk_mul_f32 v[78:79], v[78:79], v[6:7]
	v_cvt_pk_fp8_f32 v177, v76, v77
	v_cvt_pk_fp8_f32 v177, v78, v79 op_sel:[0,0,1]
	v_pk_mul_f32 v[80:81], v[80:81], v[6:7]
	v_pk_mul_f32 v[82:83], v[82:83], v[6:7]
	v_cvt_pk_fp8_f32 v178, v80, v81
	v_cvt_pk_fp8_f32 v178, v82, v83 op_sel:[0,0,1]
	v_pk_mul_f32 v[84:85], v[84:85], v[6:7]
	v_pk_mul_f32 v[86:87], v[86:87], v[6:7]
	v_cvt_pk_fp8_f32 v179, v84, v85
	v_cvt_pk_fp8_f32 v179, v86, v87 op_sel:[0,0,1]
	s_add_u32 s38, s16, 0x100000
	s_addc_u32 s39, s17, 0
	global_store_dwordx4 v5, v[176:179], s[38:39]
	v_pk_mul_f32 v[88:89], v[88:89], v[6:7]
	v_pk_mul_f32 v[90:91], v[90:91], v[6:7]
	v_cvt_pk_fp8_f32 v180, v88, v89
	v_cvt_pk_fp8_f32 v180, v90, v91 op_sel:[0,0,1]
	v_pk_mul_f32 v[92:93], v[92:93], v[6:7]
	v_pk_mul_f32 v[94:95], v[94:95], v[6:7]
	v_cvt_pk_fp8_f32 v181, v92, v93
	v_cvt_pk_fp8_f32 v181, v94, v95 op_sel:[0,0,1]
	v_pk_mul_f32 v[96:97], v[96:97], v[6:7]
	v_pk_mul_f32 v[98:99], v[98:99], v[6:7]
	v_cvt_pk_fp8_f32 v182, v96, v97
	v_cvt_pk_fp8_f32 v182, v98, v99 op_sel:[0,0,1]
	v_pk_mul_f32 v[100:101], v[100:101], v[6:7]
	v_pk_mul_f32 v[102:103], v[102:103], v[6:7]
	v_cvt_pk_fp8_f32 v183, v100, v101
	v_cvt_pk_fp8_f32 v183, v102, v103 op_sel:[0,0,1]
	s_add_u32 s38, s16, 0x140000
	s_addc_u32 s39, s17, 0
	global_store_dwordx4 v5, v[180:183], s[38:39]
	v_pk_mul_f32 v[104:105], v[104:105], v[6:7]
	v_pk_mul_f32 v[106:107], v[106:107], v[6:7]
	v_cvt_pk_fp8_f32 v184, v104, v105
	v_cvt_pk_fp8_f32 v184, v106, v107 op_sel:[0,0,1]
	v_pk_mul_f32 v[108:109], v[108:109], v[6:7]
	v_pk_mul_f32 v[110:111], v[110:111], v[6:7]
	v_cvt_pk_fp8_f32 v185, v108, v109
	v_cvt_pk_fp8_f32 v185, v110, v111 op_sel:[0,0,1]
	v_pk_mul_f32 v[112:113], v[112:113], v[6:7]
	v_pk_mul_f32 v[114:115], v[114:115], v[6:7]
	v_cvt_pk_fp8_f32 v186, v112, v113
	v_cvt_pk_fp8_f32 v186, v114, v115 op_sel:[0,0,1]
	v_pk_mul_f32 v[116:117], v[116:117], v[6:7]
	v_pk_mul_f32 v[118:119], v[118:119], v[6:7]
	v_cvt_pk_fp8_f32 v187, v116, v117
	v_cvt_pk_fp8_f32 v187, v118, v119 op_sel:[0,0,1]
	s_add_u32 s38, s16, 0x180000
	s_addc_u32 s39, s17, 0
	global_store_dwordx4 v5, v[184:187], s[38:39]
	v_pk_mul_f32 v[120:121], v[120:121], v[6:7]
	v_pk_mul_f32 v[122:123], v[122:123], v[6:7]
	v_cvt_pk_fp8_f32 v188, v120, v121
	v_cvt_pk_fp8_f32 v188, v122, v123 op_sel:[0,0,1]
	v_pk_mul_f32 v[124:125], v[124:125], v[6:7]
	v_pk_mul_f32 v[126:127], v[126:127], v[6:7]
	v_cvt_pk_fp8_f32 v189, v124, v125
	v_cvt_pk_fp8_f32 v189, v126, v127 op_sel:[0,0,1]
	v_pk_mul_f32 v[128:129], v[128:129], v[6:7]
	v_pk_mul_f32 v[130:131], v[130:131], v[6:7]
	v_cvt_pk_fp8_f32 v190, v128, v129
	v_cvt_pk_fp8_f32 v190, v130, v131 op_sel:[0,0,1]
	v_pk_mul_f32 v[132:133], v[132:133], v[6:7]
	v_pk_mul_f32 v[134:135], v[134:135], v[6:7]
	v_cvt_pk_fp8_f32 v191, v132, v133
	v_cvt_pk_fp8_f32 v191, v134, v135 op_sel:[0,0,1]
	s_add_u32 s38, s16, 0x1c0000
	s_addc_u32 s39, s17, 0
	global_store_dwordx4 v5, v[188:191], s[38:39]
	s_add_u32 s36, s22, 0x2000000
	s_addc_u32 s37, s23, 0
	global_load_dwordx4 v[72:75], v4, s[36:37]
	global_load_dwordx4 v[76:79], v4, s[36:37] offset:16
	global_load_dwordx4 v[80:83], v4, s[36:37] offset:32
	global_load_dwordx4 v[84:87], v4, s[36:37] offset:48
	s_add_u32 s36, s22, 0x2800000
	s_addc_u32 s37, s23, 0
	global_load_dwordx4 v[88:91], v4, s[36:37]
	global_load_dwordx4 v[92:95], v4, s[36:37] offset:16
	global_load_dwordx4 v[96:99], v4, s[36:37] offset:32
	global_load_dwordx4 v[100:103], v4, s[36:37] offset:48
	s_add_u32 s36, s22, 0x3000000
	s_addc_u32 s37, s23, 0
	global_load_dwordx4 v[104:107], v4, s[36:37]
	global_load_dwordx4 v[108:111], v4, s[36:37] offset:16
	global_load_dwordx4 v[112:115], v4, s[36:37] offset:32
	global_load_dwordx4 v[116:119], v4, s[36:37] offset:48
	s_add_u32 s36, s22, 0x3800000
	s_addc_u32 s37, s23, 0
	global_load_dwordx4 v[120:123], v4, s[36:37]
	global_load_dwordx4 v[124:127], v4, s[36:37] offset:16
	global_load_dwordx4 v[128:131], v4, s[36:37] offset:32
	global_load_dwordx4 v[132:135], v4, s[36:37] offset:48
	s_waitcnt vmcnt(20)
; DI void phase_tables(const Params& p, int l, int bid, int nblk) {
;     ...
;   for (int e = gtid; e < 2 * 16384 * 64; e += gn) {
;     const int which = e / (16384 * 64), r = e % (16384 * 64);
;     const float sc = which ? V_SCALE : U_SCALE;
;     const float* src = (which ? p.in[I_PV] : p.in[I_PU]) + (size_t)l * 16384 * 1024 + (size_t)r * 16;
;     u32 o[4];
; #pragma unroll
;     for (int q = 0; q < 4; ++q) {
;       const float4 a = *(const float4*)(src + q * 4);
;       int v = __builtin_amdgcn_cvt_pk_fp8_f32(a.x * sc, a.y * sc, 0, false);
;       v = __builtin_amdgcn_cvt_pk_fp8_f32(a.z * sc, a.w * sc, v, true);
;       o[q] = (u32)v;
;     }
;     uint4 ov = {o[0], o[1], o[2], o[3]};
;     *(uint4*)&dst[(size_t)e * 16] = ov;
;   }
	v_mov_b32_e32 v6, 4.0
	v_mov_b32_e32 v7, v6
	v_pk_mul_f32 v[8:9], v[8:9], v[6:7]
	v_pk_mul_f32 v[10:11], v[10:11], v[6:7]
	v_cvt_pk_fp8_f32 v148, v8, v9
	v_cvt_pk_fp8_f32 v148, v10, v11 op_sel:[0,0,1]
	v_pk_mul_f32 v[12:13], v[12:13], v[6:7]
	v_pk_mul_f32 v[14:15], v[14:15], v[6:7]
	v_cvt_pk_fp8_f32 v149, v12, v13
	v_cvt_pk_fp8_f32 v149, v14, v15 op_sel:[0,0,1]
	v_pk_mul_f32 v[16:17], v[16:17], v[6:7]
	v_pk_mul_f32 v[18:19], v[18:19], v[6:7]
	v_cvt_pk_fp8_f32 v150, v16, v17
	v_cvt_pk_fp8_f32 v150, v18, v19 op_sel:[0,0,1]
	v_pk_mul_f32 v[20:21], v[20:21], v[6:7]
	v_pk_mul_f32 v[22:23], v[22:23], v[6:7]
	v_cvt_pk_fp8_f32 v151, v20, v21
	v_cvt_pk_fp8_f32 v151, v22, v23 op_sel:[0,0,1]
	s_add_u32 s38, s16, 0x1000000
	s_addc_u32 s39, s17, 0
	global_store_dwordx4 v5, v[148:151], s[38:39]
	v_pk_mul_f32 v[24:25], v[24:25], v[6:7]
	v_pk_mul_f32 v[26:27], v[26:27], v[6:7]
	v_cvt_pk_fp8_f32 v152, v24, v25
	v_cvt_pk_fp8_f32 v152, v26, v27 op_sel:[0,0,1]
	v_pk_mul_f32 v[28:29], v[28:29], v[6:7]
	v_pk_mul_f32 v[30:31], v[30:31], v[6:7]
	v_cvt_pk_fp8_f32 v153, v28, v29
	v_cvt_pk_fp8_f32 v153, v30, v31 op_sel:[0,0,1]
	v_pk_mul_f32 v[32:33], v[32:33], v[6:7]
	v_pk_mul_f32 v[34:35], v[34:35], v[6:7]
	v_cvt_pk_fp8_f32 v154, v32, v33
	v_cvt_pk_fp8_f32 v154, v34, v35 op_sel:[0,0,1]
	v_pk_mul_f32 v[36:37], v[36:37], v[6:7]
	v_pk_mul_f32 v[38:39], v[38:39], v[6:7]
	v_cvt_pk_fp8_f32 v155, v36, v37
	v_cvt_pk_fp8_f32 v155, v38, v39 op_sel:[0,0,1]
	s_add_u32 s38, s16, 0x1040000
	s_addc_u32 s39, s17, 0
	global_store_dwordx4 v5, v[152:155], s[38:39]
	v_pk_mul_f32 v[40:41], v[40:41], v[6:7]
	v_pk_mul_f32 v[42:43], v[42:43], v[6:7]
	v_cvt_pk_fp8_f32 v156, v40, v41
	v_cvt_pk_fp8_f32 v156, v42, v43 op_sel:[0,0,1]
	v_pk_mul_f32 v[44:45], v[44:45], v[6:7]
	v_pk_mul_f32 v[46:47], v[46:47], v[6:7]
	v_cvt_pk_fp8_f32 v157, v44, v45
	v_cvt_pk_fp8_f32 v157, v46, v47 op_sel:[0,0,1]
	v_pk_mul_f32 v[48:49], v[48:49], v[6:7]
	v_pk_mul_f32 v[50:51], v[50:51], v[6:7]
	v_cvt_pk_fp8_f32 v158, v48, v49
	v_cvt_pk_fp8_f32 v158, v50, v51 op_sel:[0,0,1]
	v_pk_mul_f32 v[52:53], v[52:53], v[6:7]
	v_pk_mul_f32 v[54:55], v[54:55], v[6:7]
	v_cvt_pk_fp8_f32 v159, v52, v53
	v_cvt_pk_fp8_f32 v159, v54, v55 op_sel:[0,0,1]
	s_add_u32 s38, s16, 0x1080000
	s_addc_u32 s39, s17, 0
	global_store_dwordx4 v5, v[156:159], s[38:39]
	v_pk_mul_f32 v[56:57], v[56:57], v[6:7]
	v_pk_mul_f32 v[58:59], v[58:59], v[6:7]
	v_cvt_pk_fp8_f32 v160, v56, v57
	v_cvt_pk_fp8_f32 v160, v58, v59 op_sel:[0,0,1]
	v_pk_mul_f32 v[60:61], v[60:61], v[6:7]
	v_pk_mul_f32 v[62:63], v[62:63], v[6:7]
	v_cvt_pk_fp8_f32 v161, v60, v61
	v_cvt_pk_fp8_f32 v161, v62, v63 op_sel:[0,0,1]
	v_pk_mul_f32 v[64:65], v[64:65], v[6:7]
	v_pk_mul_f32 v[66:67], v[66:67], v[6:7]
	v_cvt_pk_fp8_f32 v162, v64, v65
	v_cvt_pk_fp8_f32 v162, v66, v67 op_sel:[0,0,1]
	v_pk_mul_f32 v[68:69], v[68:69], v[6:7]
	v_pk_mul_f32 v[70:71], v[70:71], v[6:7]
	v_cvt_pk_fp8_f32 v163, v68, v69
	v_cvt_pk_fp8_f32 v163, v70, v71 op_sel:[0,0,1]
	s_add_u32 s38, s16, 0x10c0000
	s_addc_u32 s39, s17, 0
	global_store_dwordx4 v5, v[160:163], s[38:39]
	s_waitcnt vmcnt(4)
	v_mov_b32_e32 v6, 4.0
	v_mov_b32_e32 v7, v6
	v_pk_mul_f32 v[72:73], v[72:73], v[6:7]
	v_pk_mul_f32 v[74:75], v[74:75], v[6:7]
	v_cvt_pk_fp8_f32 v176, v72, v73
	v_cvt_pk_fp8_f32 v176, v74, v75 op_sel:[0,0,1]
	v_pk_mul_f32 v[76:77], v[76:77], v[6:7]
	v_pk_mul_f32 v[78:79], v[78:79], v[6:7]
	v_cvt_pk_fp8_f32 v177, v76, v77
	v_cvt_pk_fp8_f32 v177, v78, v79 op_sel:[0,0,1]
	v_pk_mul_f32 v[80:81], v[80:81], v[6:7]
	v_pk_mul_f32 v[82:83], v[82:83], v[6:7]
	v_cvt_pk_fp8_f32 v178, v80, v81
	v_cvt_pk_fp8_f32 v178, v82, v83 op_sel:[0,0,1]
	v_pk_mul_f32 v[84:85], v[84:85], v[6:7]
	v_pk_mul_f32 v[86:87], v[86:87], v[6:7]
	v_cvt_pk_fp8_f32 v179, v84, v85
	v_cvt_pk_fp8_f32 v179, v86, v87 op_sel:[0,0,1]
	s_add_u32 s38, s16, 0x1100000
	s_addc_u32 s39, s17, 0
	global_store_dwordx4 v5, v[176:179], s[38:39]
	v_pk_mul_f32 v[88:89], v[88:89], v[6:7]
	v_pk_mul_f32 v[90:91], v[90:91], v[6:7]
	v_cvt_pk_fp8_f32 v180, v88, v89
	v_cvt_pk_fp8_f32 v180, v90, v91 op_sel:[0,0,1]
	v_pk_mul_f32 v[92:93], v[92:93], v[6:7]
	v_pk_mul_f32 v[94:95], v[94:95], v[6:7]
	v_cvt_pk_fp8_f32 v181, v92, v93
	v_cvt_pk_fp8_f32 v181, v94, v95 op_sel:[0,0,1]
	v_pk_mul_f32 v[96:97], v[96:97], v[6:7]
	v_pk_mul_f32 v[98:99], v[98:99], v[6:7]
	v_cvt_pk_fp8_f32 v182, v96, v97
	v_cvt_pk_fp8_f32 v182, v98, v99 op_sel:[0,0,1]
	v_pk_mul_f32 v[100:101], v[100:101], v[6:7]
	v_pk_mul_f32 v[102:103], v[102:103], v[6:7]
	v_cvt_pk_fp8_f32 v183, v100, v101
	v_cvt_pk_fp8_f32 v183, v102, v103 op_sel:[0,0,1]
	s_add_u32 s38, s16, 0x1140000
	s_addc_u32 s39, s17, 0
	global_store_dwordx4 v5, v[180:183], s[38:39]
	v_pk_mul_f32 v[104:105], v[104:105], v[6:7]
	v_pk_mul_f32 v[106:107], v[106:107], v[6:7]
	v_cvt_pk_fp8_f32 v184, v104, v105
	v_cvt_pk_fp8_f32 v184, v106, v107 op_sel:[0,0,1]
	v_pk_mul_f32 v[108:109], v[108:109], v[6:7]
	v_pk_mul_f32 v[110:111], v[110:111], v[6:7]
	v_cvt_pk_fp8_f32 v185, v108, v109
	v_cvt_pk_fp8_f32 v185, v110, v111 op_sel:[0,0,1]
	v_pk_mul_f32 v[112:113], v[112:113], v[6:7]
	v_pk_mul_f32 v[114:115], v[114:115], v[6:7]
	v_cvt_pk_fp8_f32 v186, v112, v113
	v_cvt_pk_fp8_f32 v186, v114, v115 op_sel:[0,0,1]
	v_pk_mul_f32 v[116:117], v[116:117], v[6:7]
	v_pk_mul_f32 v[118:119], v[118:119], v[6:7]
	v_cvt_pk_fp8_f32 v187, v116, v117
	v_cvt_pk_fp8_f32 v187, v118, v119 op_sel:[0,0,1]
	s_add_u32 s38, s16, 0x1180000
	s_addc_u32 s39, s17, 0
	global_store_dwordx4 v5, v[184:187], s[38:39]
	v_pk_mul_f32 v[120:121], v[120:121], v[6:7]
	v_pk_mul_f32 v[122:123], v[122:123], v[6:7]
	v_cvt_pk_fp8_f32 v188, v120, v121
	v_cvt_pk_fp8_f32 v188, v122, v123 op_sel:[0,0,1]
	v_pk_mul_f32 v[124:125], v[124:125], v[6:7]
	v_pk_mul_f32 v[126:127], v[126:127], v[6:7]
	v_cvt_pk_fp8_f32 v189, v124, v125
	v_cvt_pk_fp8_f32 v189, v126, v127 op_sel:[0,0,1]
	v_pk_mul_f32 v[128:129], v[128:129], v[6:7]
	v_pk_mul_f32 v[130:131], v[130:131], v[6:7]
	v_cvt_pk_fp8_f32 v190, v128, v129
	v_cvt_pk_fp8_f32 v190, v130, v131 op_sel:[0,0,1]
	v_pk_mul_f32 v[132:133], v[132:133], v[6:7]
	v_pk_mul_f32 v[134:135], v[134:135], v[6:7]
	v_cvt_pk_fp8_f32 v191, v132, v133
	v_cvt_pk_fp8_f32 v191, v134, v135 op_sel:[0,0,1]
	s_add_u32 s38, s16, 0x11c0000
	s_addc_u32 s39, s17, 0
	global_store_dwordx4 v5, v[188:191], s[38:39]
